# layer-1 GS table job at the start of the up phase moved from workgroups 0-19 (which carry a fifth half-unit) to workgroups 64-83
# speedup vs baseline: 1.0033x; 1.0033x over previous
.LBB0_854:
	s_andn2_b64 vcc, exec, s[0:1]
	v_readlane_b32 s0, v254, 56
	v_readlane_b32 s1, v254, 57
	s_nop 1
	v_cndmask_b32_e64 v0, 0, 1, s[0:1]
	v_cmp_ne_u32_e64 s[4:5], 1, v0
	s_cbranch_vccnz .LBB0_1018
	v_readlane_b32 s1, v254, 26
	s_and_b64 vcc, exec, s[4:5]
	s_nop 0
	v_mov_b32_e32 v0, s1
	ds_read_b64 v[0:1], v0
	s_waitcnt lgkmcnt(0)
	v_readfirstlane_b32 s24, v1
	v_readfirstlane_b32 s25, v0
	s_cbranch_vccnz .LBB0_867
	v_mov_b32_e32 v0, v224
	v_readlane_b32 s0, v254, 0
	v_readlane_b32 s2, v254, 1
	v_mov_b32_e32 v1, s1
	ds_read_b64 v[2:3], v1
	v_lshl_add_u32 v0, s0, 9, v0
	v_add_u32_e32 v0, 0xffff8000, v0
	s_movk_i32 s0, 0x2800
	v_cmp_gt_u32_e32 vcc, s0, v0
	s_waitcnt lgkmcnt(0)
	v_readfirstlane_b32 s9, v3
	v_readfirstlane_b32 s8, v2
	s_and_saveexec_b64 s[0:1], vcc
	s_cbranch_execz .LBB0_868
	s_lshl_b32 s2, s2, 9
	s_add_u32 s6, s8, 0x2ec2000
	v_ashrrev_i32_e32 v1, 31, v0
	s_addc_u32 s7, s9, 0
	v_lshl_add_u64 v[2:3], v[0:1], 2, s[8:9]
	s_mov_b64 s[8:9], 0x2f33000
	s_ashr_i32 s3, s2, 31
	v_lshl_add_u64 v[2:3], v[2:3], 0, s[8:9]
	s_lshl_b64 s[8:9], s[2:3], 2
	s_mov_b64 s[10:11], 0
	s_branch .LBB0_859
